# grid barriers: mid-round arriver of each XCD starts an early L2 writeback
# baseline (speedup 1.0000x reference)
; __device__ __forceinline__ unsigned xb_ld(unsigned* p)              { return __hip_atomic_load(p, __ATOMIC_RELAXED, __HIP_MEMORY_SCOPE_AGENT); }
; __device__ __forceinline__ unsigned xb_add(unsigned* p, unsigned v) { return __hip_atomic_fetch_add(p, v, __ATOMIC_RELAXED, __HIP_MEMORY_SCOPE_AGENT); }
; #define XB_SPIN(cond, bar) do { unsigned _sp = 0; while (cond) { __builtin_amdgcn_s_sleep(1); \
;     if ((++_sp & 255u) == 0u) { if (xb_ld(&(bar)[XB_TMO])) break; if (_sp > XB_SPIN_CAP) { atomicAdd(&(bar)[XB_TMO], 1u); break; } } } } while (0)
; __device__ __forceinline__ void xcd_barrier(const XcdBarrier& b) {
;     ...
;         const unsigned old = xb_add(&bar[XB_XSUB(b.x)], 1u);
;         const unsigned gen = old / nloc;
;         if (old + 1u == (gen + 1u) * nloc) {
;             __builtin_amdgcn_fence(__ATOMIC_RELEASE, "agent");
;             asm volatile("s_waitcnt vmcnt(0)" ::: "memory");
;             const unsigned og = xb_add(&bar[XB_TOP], 1u);
;             const unsigned tg = og / nx;
;             if (og + 1u == (tg + 1u) * nx) xb_add(&bar[XB_TOPGEN], 1u);
;             else XB_SPIN(xb_ld(&bar[XB_TOPGEN]) == tg, bar);
;             __builtin_amdgcn_fence(__ATOMIC_ACQUIRE, "agent");
;             xb_add(&bar[XB_XGEN(b.x)], 1u);
;             asm volatile("s_waitcnt vmcnt(0)" ::: "memory");
;         } else {
;             XB_SPIN(xb_ld(&bar[XB_XGEN(b.x)]) == gen, bar);
;             __builtin_amdgcn_fence(__ATOMIC_ACQUIRE, "agent");
;             asm volatile("s_waitcnt vmcnt(0)" ::: "memory");
;         }
.LBB0_91:
	s_or_b64 exec, exec, s[12:13]
	v_cvt_f32_u32_e32 v5, v3
	s_waitcnt vmcnt(0)
	v_readfirstlane_b32 s3, v4
	v_sub_u32_e32 v4, 0, v3
	v_rcp_iflag_f32_e32 v5, v5
	v_add_u32_e32 v6, s3, v2
	v_mul_f32_e32 v5, 0x4f7ffffe, v5
	v_cvt_u32_f32_e32 v5, v5
	v_mul_lo_u32 v2, v4, v5
	v_mul_hi_u32 v2, v5, v2
	v_add_u32_e32 v2, v5, v2
	v_mul_hi_u32 v2, v6, v2
	v_mul_lo_u32 v4, v2, v3
	v_sub_u32_e32 v4, v6, v4
	v_add_u32_e32 v5, 1, v2
	v_cmp_ge_u32_e32 vcc, v4, v3
	s_nop 1
	v_cndmask_b32_e32 v2, v2, v5, vcc
	v_sub_u32_e32 v5, v4, v3
	v_cndmask_b32_e32 v4, v4, v5, vcc
	v_add_u32_e32 v5, 1, v2
	v_cmp_ge_u32_e32 vcc, v4, v3
	v_add_u32_e32 v4, 1, v6
	s_nop 0
	v_cndmask_b32_e32 v2, v2, v5, vcc
	v_mul_lo_u32 v5, v3, v2
	v_add_u32_e32 v3, v5, v3
	v_cmp_ne_u32_e32 vcc, v4, v3
	s_and_saveexec_b64 s[10:11], vcc
	s_xor_b64 s[10:11], exec, s[10:11]
	s_cbranch_execz .LBB0_105
	s_waitcnt lgkmcnt(0)
	v_sub_u32_e32 v8, v6, v5
	v_sub_u32_e32 v9, v3, v5
	v_lshrrev_b32_e32 v9, 1, v9
	v_cmp_eq_u32_e32 vcc, v8, v9
	s_and_saveexec_b64 s[12:13], vcc
	s_cbranch_execz .Lwb_1
	buffer_wbl2 sc1
.Lwb_1:
	s_or_b64 exec, exec, s[12:13]
	v_mov_b32_e32 v1, 0x2000
	global_load_dword v1, v1, s[8:9] offset:1024 sc1
	s_add_u32 s16, s8, 0x2400
	s_addc_u32 s17, s9, 0
	s_waitcnt vmcnt(0)
	v_cmp_eq_u32_e32 vcc, v1, v2
	s_and_saveexec_b64 s[12:13], vcc
	s_cbranch_execz .LBB0_104
	s_add_u32 s14, s6, 0x40200
	s_addc_u32 s15, s7, 0
	s_mov_b32 s3, 1
	s_mov_b64 s[20:21], 0
	v_mov_b32_e32 v1, 0
	s_branch .LBB0_95

; __device__ __forceinline__ unsigned xb_ld(unsigned* p)              { return __hip_atomic_load(p, __ATOMIC_RELAXED, __HIP_MEMORY_SCOPE_AGENT); }
; __device__ __forceinline__ unsigned xb_add(unsigned* p, unsigned v) { return __hip_atomic_fetch_add(p, v, __ATOMIC_RELAXED, __HIP_MEMORY_SCOPE_AGENT); }
; #define XB_SPIN(cond, bar) do { unsigned _sp = 0; while (cond) { __builtin_amdgcn_s_sleep(1); \
;     if ((++_sp & 255u) == 0u) { if (xb_ld(&(bar)[XB_TMO])) break; if (_sp > XB_SPIN_CAP) { atomicAdd(&(bar)[XB_TMO], 1u); break; } } } } while (0)
; __device__ __forceinline__ void xcd_barrier(const XcdBarrier& b) {
;     ...
;         const unsigned old = xb_add(&bar[XB_XSUB(b.x)], 1u);
;         const unsigned gen = old / nloc;
;         if (old + 1u == (gen + 1u) * nloc) {
;             __builtin_amdgcn_fence(__ATOMIC_RELEASE, "agent");
;             asm volatile("s_waitcnt vmcnt(0)" ::: "memory");
;             const unsigned og = xb_add(&bar[XB_TOP], 1u);
;             const unsigned tg = og / nx;
;             if (og + 1u == (tg + 1u) * nx) xb_add(&bar[XB_TOPGEN], 1u);
;             else XB_SPIN(xb_ld(&bar[XB_TOPGEN]) == tg, bar);
;             __builtin_amdgcn_fence(__ATOMIC_ACQUIRE, "agent");
;             xb_add(&bar[XB_XGEN(b.x)], 1u);
;             asm volatile("s_waitcnt vmcnt(0)" ::: "memory");
;         } else {
;             XB_SPIN(xb_ld(&bar[XB_XGEN(b.x)]) == gen, bar);
;             __builtin_amdgcn_fence(__ATOMIC_ACQUIRE, "agent");
;             asm volatile("s_waitcnt vmcnt(0)" ::: "memory");
;         }
.LBB0_303:
	s_or_b64 exec, exec, s[12:13]
	v_cvt_f32_u32_e32 v6, v4
	s_waitcnt vmcnt(0)
	v_readfirstlane_b32 s3, v5
	v_sub_u32_e32 v5, 0, v4
	v_rcp_iflag_f32_e32 v6, v6
	v_add_u32_e32 v7, s3, v3
	v_mul_f32_e32 v6, 0x4f7ffffe, v6
	v_cvt_u32_f32_e32 v6, v6
	v_mul_lo_u32 v3, v5, v6
	v_mul_hi_u32 v3, v6, v3
	v_add_u32_e32 v3, v6, v3
	v_mul_hi_u32 v3, v7, v3
	v_mul_lo_u32 v5, v3, v4
	v_sub_u32_e32 v5, v7, v5
	v_add_u32_e32 v6, 1, v3
	v_cmp_ge_u32_e32 vcc, v5, v4
	s_nop 1
	v_cndmask_b32_e32 v3, v3, v6, vcc
	v_sub_u32_e32 v6, v5, v4
	v_cndmask_b32_e32 v5, v5, v6, vcc
	v_add_u32_e32 v6, 1, v3
	v_cmp_ge_u32_e32 vcc, v5, v4
	v_add_u32_e32 v5, 1, v7
	s_nop 0
	v_cndmask_b32_e32 v3, v3, v6, vcc
	v_mul_lo_u32 v6, v4, v3
	v_add_u32_e32 v4, v6, v4
	v_cmp_ne_u32_e32 vcc, v5, v4
	s_and_saveexec_b64 s[10:11], vcc
	s_xor_b64 s[10:11], exec, s[10:11]
	s_cbranch_execz .LBB0_317
	s_waitcnt lgkmcnt(0)
	v_sub_u32_e32 v8, v7, v6
	v_sub_u32_e32 v9, v4, v6
	v_lshrrev_b32_e32 v9, 1, v9
	v_cmp_eq_u32_e32 vcc, v8, v9
	s_and_saveexec_b64 s[12:13], vcc
	s_cbranch_execz .Lwb_3
	buffer_wbl2 sc1
.Lwb_3:
	s_or_b64 exec, exec, s[12:13]
	v_mov_b32_e32 v2, 0x2000
	global_load_dword v2, v2, s[8:9] offset:1024 sc1
	s_add_u32 s16, s8, 0x2400
	s_addc_u32 s17, s9, 0
	s_waitcnt vmcnt(0)
	v_cmp_eq_u32_e32 vcc, v2, v3
	s_and_saveexec_b64 s[12:13], vcc
	s_cbranch_execz .LBB0_316
	s_add_u32 s14, s6, 0x40200
	s_addc_u32 s15, s7, 0
	s_mov_b32 s3, 1
	s_mov_b64 s[20:21], 0
	v_mov_b32_e32 v2, 0
	s_branch .LBB0_307

; __device__ __forceinline__ unsigned xb_ld(unsigned* p)              { return __hip_atomic_load(p, __ATOMIC_RELAXED, __HIP_MEMORY_SCOPE_AGENT); }
; #define XB_SPIN(cond, bar) do { unsigned _sp = 0; while (cond) { __builtin_amdgcn_s_sleep(1); \
;     if ((++_sp & 255u) == 0u) { if (xb_ld(&(bar)[XB_TMO])) break; if (_sp > XB_SPIN_CAP) { atomicAdd(&(bar)[XB_TMO], 1u); break; } } } } while (0)
; __device__ __forceinline__ void xcd_barrier(const XcdBarrier& b) {
;     ...
;         } else {
;             XB_SPIN(xb_ld(&bar[XB_XGEN(b.x)]) == gen, bar);
;             __builtin_amdgcn_fence(__ATOMIC_ACQUIRE, "agent");
;             asm volatile("s_waitcnt vmcnt(0)" ::: "memory");
;         }
.Lwb_5:
	s_or_b64 exec, exec, s[12:13]
	v_mov_b32_e32 v1, 0x2000
	global_load_dword v1, v1, s[8:9] offset:1024 sc1
	s_add_u32 s16, s8, 0x2400
	s_addc_u32 s17, s9, 0
	s_waitcnt vmcnt(0)
	v_cmp_eq_u32_e32 vcc, v1, v2
	s_and_saveexec_b64 s[12:13], vcc
	s_cbranch_execz .LBB0_547
	s_add_u32 s14, s6, 0x40200
	s_addc_u32 s15, s7, 0
	s_mov_b32 s3, 1
	s_mov_b64 s[18:19], 0
	v_mov_b32_e32 v1, 0
	s_branch .LBB0_538
